# stack6: stack5 + decode items: gate word and sub-LN weights loaded ahead of the K/V stream, next item's block-table entry prefetched one item ahead
# speedup vs baseline: 1.0083x; 1.0083x over previous
.LBB0_381:
	v_readlane_b32 s0, v247, 37
	s_cmp_lg_u32 s88, s0
	s_cbranch_scc1 .LBB0_406
	v_readlane_b32 s6, v247, 35
	s_mov_b64 s[74:75], s[40:41]
	s_mov_b64 s[2:3], s[60:61]
	s_mov_b64 s[4:5], s[70:71]
	s_mov_b64 s[22:23], s[42:43]
	s_mov_b64 s[50:51], s[46:47]
	v_readlane_b32 s7, v247, 36
	v_mbcnt_lo_u32_b32 v0, -1, 0
	v_mbcnt_hi_u32_b32 v0, -1, v0
	v_readlane_b32 s0, v247, 42
	v_add_u32_e32 v0, s94, v0
	v_readlane_b32 s1, v247, 43
	s_andn2_b64 vcc, exec, s[0:1]
	v_readfirstlane_b32 s0, v0
	s_cbranch_vccnz .LBB0_406
	s_add_u32 s18, s6, 0x3400000
	v_and_b32_e32 v5, 15, v0
	s_addc_u32 s19, s7, 0
	v_bfe_u32 v1, v0, 4, 2
	v_lshlrev_b32_e32 v196, 2, v5
	s_add_u32 s72, s6, 0x6a00000
	v_or_b32_e32 v7, v196, v1
	s_addc_u32 s73, s7, 0
	v_lshlrev_b32_e32 v201, 2, v7
	v_bfe_u32 v7, v0, 2, 4
	v_lshlrev_b32_e32 v10, 2, v0
	s_add_u32 s76, s6, 0xec00000
	v_lshlrev_b32_e32 v8, 11, v7
	v_mov_b32_e32 v9, v2
	v_and_b32_e32 v200, 12, v10
	s_addc_u32 s77, s7, 0
	s_ashr_i32 s70, s0, 6
	v_lshl_add_u64 v[8:9], s[74:75], 0, v[8:9]
	v_lshlrev_b32_e32 v10, 2, v200
	v_mov_b32_e32 v11, v2
	s_lshl_b32 s16, s70, 12
	s_lshl_b32 s27, s70, 1
	v_lshl_add_u64 v[202:203], v[8:9], 0, v[10:11]
	v_lshlrev_b32_e32 v8, 13, v1
	v_mov_b32_e32 v9, v2
	v_lshl_add_u64 v[8:9], s[22:23], 0, v[8:9]
	v_lshlrev_b32_e32 v10, 4, v5
	s_cmp_eq_u32 s70, 7
	v_lshl_add_u64 v[206:207], v[8:9], 0, v[10:11]
	s_cselect_b64 s[20:21], -1, 0
	s_add_u32 s86, s4, 0x841e000
	v_lshl_add_u64 v[8:9], s[4:5], 0, v[10:11]
	s_mov_b64 s[0:1], 0x861e000
	v_and_b32_e32 v3, 63, v0
	v_and_b32_e32 v197, 7, v0
	s_addc_u32 s87, s5, 0
	v_lshl_add_u64 v[208:209], v[8:9], 0, s[0:1]
	v_and_b32_e32 v0, 48, v0
	s_lshl_b32 s1, s70, 13
	v_lshlrev_b32_e32 v6, 2, v1
	v_lshlrev_b32_e32 v204, 11, v1
	s_add_i32 s1, s1, 0
	v_lshlrev_b32_e32 v1, 9, v5
	v_lshlrev_b32_e32 v0, 2, v0
	v_add3_u32 v230, s1, v1, v0
	v_lshlrev_b32_e32 v0, 3, v3
	v_mov_b32_e32 v1, v2
	v_lshl_add_u64 v[210:211], s[2:3], 0, v[0:1]
	s_add_i32 s2, s70, 8
	v_lshlrev_b32_e32 v199, 3, v5
	s_lshl_b32 s0, s70, 7
	v_add_u32_e32 v231, 0, v0
	s_lshl_b32 s1, s2, 3
	v_or_b32_e32 v0, 1, v6
	s_lshl_b32 s95, s2, 9
	s_add_i32 s2, s16, 0
	v_and_b32_e32 v4, 64, v199
	s_add_i32 s0, s0, 0
	v_min_u32_e32 v234, 7, v0
	v_or_b32_e32 v0, 2, v6
	v_or_b32_e32 v1, 3, v6
	s_lshl_b32 s67, s70, 9
	s_add_i32 s2, s2, 0x12000
	v_cmp_gt_u32_e64 s[14:15], 8, v5
	v_lshlrev_b32_e32 v198, 9, v7
	v_min_u32_e32 v205, 7, v7
	v_cmp_gt_u32_e64 s[4:5], 16, v3
	s_add_i32 s0, s0, 0x10000
	v_lshlrev_b32_e32 v232, 1, v3
	v_min_u32_e32 v233, 7, v6
	v_min_u32_e32 v235, 7, v0
	v_min_u32_e32 v236, 7, v1
	v_cmp_gt_u32_e64 s[6:7], v6, v197
	v_cmp_lt_u32_e64 s[8:9], v6, v197
	v_cmp_gt_u32_e64 s[10:11], v0, v197
	v_cmp_gt_u32_e64 s[12:13], v1, v197
	s_lshl_b32 s66, s70, 3
	s_add_i32 s28, s67, 0x2000
	s_add_i32 s29, s67, 0x4000
	s_add_i32 s24, s67, 0x6000
	s_add_i32 s84, s67, 0x8000
	s_add_i32 s85, s67, 0xa000
	s_add_i32 s26, s67, 0xc000
	s_add_i32 s94, s67, 0xe000
	s_add_i32 s96, s67, 0x3000
	s_add_i32 s97, s67, 0x5000
	s_add_i32 s34, s67, 0x7000
	s_add_i32 s35, s67, 0x9000
	s_add_i32 s30, s67, 0xb000
	s_add_i32 s31, s67, 0xd000
	s_add_i32 s68, s67, 0xf000
	v_lshl_add_u32 v237, v3, 4, s2
	v_lshlrev_b32_e32 v212, 1, v4
	v_mov_b32_e32 v213, v2
	v_lshlrev_b32_e32 v214, 1, v6
	v_mov_b32_e32 v215, v2
	v_readlane_b32 s69, v247, 12
	v_readlane_b32 s101, v247, 10
	s_nop 3
	s_ashr_i32 s2, s69, 2
	s_lshl_b32 s2, s2, 4
	s_add_i32 s2, s2, s27
	s_ashr_i32 s3, s2, 31
	s_lshl_b64 s[2:3], s[2:3], 2
	s_add_u32 s2, s50, s2
	s_addc_u32 s3, s51, s3
	global_load_dwordx2 v[250:251], v2, s[2:3]
	global_load_dwordx2 v[254:255], v[210:211], off
	s_branch .LBB0_385

.Llam_done:
	v_or_b32_e32 v3, s62, v232
	v_lshlrev_b32_e32 v3, 1, v3
	v_add_f32_e32 v32, s2, v229
	s_add_i32 s2, s25, s70
	s_ashr_i32 s3, s2, 31
	s_lshl_b64 s[16:17], s[2:3], 10
	s_add_u32 s16, s72, s16
	s_addc_u32 s17, s73, s17
	s_mov_b32 s16, 0xf800000
	s_lshl_b64 s[2:3], s[2:3], 11
	s_add_u32 s2, s76, s2
	s_addc_u32 s3, s77, s3
	s_waitcnt vmcnt(0)
	v_lshlrev_b32_e32 v30, 16, v252
	v_and_b32_e32 v31, 0xffff0000, v252
	v_pk_fma_f32 v[0:1], v[4:5], v[6:7], v[0:1] op_sel_hi:[0,1,1]
	s_waitcnt lgkmcnt(1)
	v_pk_fma_f32 v[4:5], v[20:21], v[22:23], v[18:19] op_sel_hi:[0,1,1]
	s_waitcnt lgkmcnt(0)
	v_pk_fma_f32 v[4:5], v[24:25], v[26:27], v[4:5] op_sel_hi:[0,1,1]
	v_pk_fma_f32 v[0:1], v[8:9], v[10:11], v[0:1] op_sel_hi:[0,1,1]
	v_pk_mul_f32 v[4:5], v[28:29], v[4:5] op_sel_hi:[0,1]
	v_pk_fma_f32 v[0:1], v[12:13], v[14:15], v[0:1] op_sel_hi:[0,1,1]
	v_pk_mul_f32 v[4:5], v[4:5], v[32:33] op_sel_hi:[1,0]
	s_nop 0
	v_pk_fma_f32 v[0:1], v[16:17], v[0:1], v[4:5] op_sel_hi:[0,1,1] neg_lo:[0,0,1] neg_hi:[0,0,1]
	v_pk_mul_f32 v[4:5], v[0:1], v[0:1]
	s_nop 0
	v_add_f32_e32 v4, v4, v5
	s_nop 1
	v_add_f32_dpp v4, v4, v4 quad_perm:[1,0,3,2] row_mask:0xf bank_mask:0xf bound_ctrl:1
	s_nop 1
	v_add_f32_dpp v4, v4, v4 quad_perm:[2,3,0,1] row_mask:0xf bank_mask:0xf bound_ctrl:1
	s_nop 1
	v_add_f32_dpp v4, v4, v4 row_half_mirror row_mask:0xf bank_mask:0xf bound_ctrl:1
	s_nop 1
	v_add_f32_dpp v4, v4, v4 row_mirror row_mask:0xf bank_mask:0xf bound_ctrl:1
	v_mov_b32_e32 v5, v4
	s_nop 1
	v_permlane16_swap_b32_e32 v4, v5
	v_add_f32_e32 v4, v4, v5
	v_mov_b32_e32 v5, v4
	s_nop 1
	v_permlane32_swap_b32_e32 v4, v5
	v_add_f32_e32 v4, v4, v5
	v_fmamk_f32 v4, v4, 0x3c000000, v224
	v_cmp_gt_f32_e32 vcc, s16, v4
	v_mul_f32_e32 v5, 0x4f800000, v4
	s_nop 0
	v_cndmask_b32_e32 v4, v4, v5, vcc
	v_sqrt_f32_e32 v5, v4
	s_nop 0
	v_add_u32_e32 v6, -1, v5
	v_fma_f32 v7, -v6, v5, v4
	v_cmp_ge_f32_e64 s[16:17], 0, v7
	v_add_u32_e32 v7, 1, v5
	s_nop 0
	v_cndmask_b32_e64 v6, v5, v6, s[16:17]
	v_fma_f32 v5, -v7, v5, v4
	v_cmp_lt_f32_e64 s[16:17], 0, v5
	s_nop 1
	v_cndmask_b32_e64 v5, v6, v7, s[16:17]
	v_mul_f32_e32 v6, 0x37800000, v5
	v_cndmask_b32_e32 v5, v5, v6, vcc
	v_cmp_class_f32_e32 vcc, v4, v225
	s_nop 1
	v_cndmask_b32_e32 v4, v5, v4, vcc
	v_div_scale_f32 v5, s[16:17], v4, v4, 1.0
	v_rcp_f32_e32 v6, v5
	s_movk_i32 s16, 0x7fff
	v_fma_f32 v7, -v5, v6, 1.0
	v_fmac_f32_e32 v6, v7, v6
	v_div_scale_f32 v7, vcc, 1.0, v4, 1.0
	v_mul_f32_e32 v8, v7, v6
	v_fma_f32 v9, -v5, v8, v7
	v_fmac_f32_e32 v8, v9, v6
	v_fma_f32 v5, -v5, v8, v7
	v_div_fmas_f32 v5, v5, v6, v8
	v_div_fixup_f32 v4, v5, v4, 1.0
	v_pk_mul_f32 v[0:1], v[0:1], v[4:5] op_sel_hi:[1,0]
	v_pk_mul_f32 v[0:1], v[254:255], v[0:1]
	s_nop 0
	v_pk_mul_f32 v[0:1], v[0:1], v[30:31]
	s_nop 0
	v_and_b32_sdwa v5, v0, v226 dst_sel:DWORD dst_unused:UNUSED_PAD src0_sel:WORD_1 src1_sel:DWORD
	v_and_b32_sdwa v4, v1, v226 dst_sel:DWORD dst_unused:UNUSED_PAD src0_sel:WORD_1 src1_sel:DWORD
	v_add3_u32 v0, v0, v5, s16
	v_add3_u32 v1, v1, v4, s16
	v_lshrrev_b32_e32 v0, 16, v0
	s_mov_b32 s16, 0xffff0000
	v_and_or_b32 v0, v1, s16, v0
	global_store_dword v3, v0, s[2:3]
	v_readlane_b32 s2, v247, 10
	s_add_i32 s69, s69, s2
	s_cmpk_lt_i32 s69, 0x200
	s_barrier
	s_cbranch_scc0 .LBB0_405
.LBB0_385:
	s_ashr_i32 s2, s69, 2
	s_lshl_b32 s63, s2, 3
	s_lshl_b32 s2, s2, 4
	s_lshl_b32 s3, s69, 7
	s_add_i32 s2, s2, s27
	s_and_b32 s62, s3, 0x180
	s_ashr_i32 s3, s2, 31
	s_add_i32 s25, s63, 0x4000
	s_lshl_b32 s64, s62, 1
	s_lshl_b64 s[2:3], s[2:3], 2
	s_add_u32 s2, s50, s2
	s_addc_u32 s3, s51, s3
	s_add_i32 s100, s69, s101
	s_lshl_b32 s78, s101, 4
	s_cmpk_lt_i32 s100, 0x200
	s_cselect_b32 s78, s78, 0
	s_add_u32 s2, s2, s78
	s_addc_u32 s3, s3, 0
	s_add_i32 vcc_lo, s25, s70
	s_ashr_i32 vcc_hi, vcc_lo, 31
	s_lshl_b64 vcc, vcc, 10
	s_add_u32 vcc_lo, s72, vcc_lo
	s_addc_u32 vcc_hi, s73, vcc_hi
	v_or_b32_e32 v253, s62, v232
	v_lshlrev_b32_e32 v253, 1, v253
	s_waitcnt vmcnt(1)
	v_readfirstlane_b32 s16, v250
	v_readfirstlane_b32 s100, v251
	global_load_dword v252, v253, vcc
	global_load_dwordx2 v[250:251], v2, s[2:3]
	v_or_b32_e32 v4, s25, v197
	v_ashrrev_i32_e32 v5, 31, v4
	v_lshlrev_b64 v[4:5], 10, v[4:5]
	v_lshl_add_u64 v[4:5], s[18:19], 0, v[4:5]
	s_lshl_b32 s44, s62, 2
	v_lshl_add_u64 v[4:5], v[4:5], 0, s[64:65]
	v_lshl_add_u64 v[4:5], v[4:5], 0, v[212:213]
	v_lshl_add_u64 v[4:5], v[4:5], 0, v[214:215]
	global_load_dwordx2 v[6:7], v[4:5], off
	global_load_dwordx2 v[8:9], v[4:5], off offset:32
	global_load_dwordx2 v[148:149], v[4:5], off offset:64
	s_nop 0
	global_load_dwordx2 v[4:5], v[4:5], off offset:96
	v_mov_b32_e32 v3, v2
	v_mov_b32_e32 v217, 0
	v_mov_b32_e32 v216, 0xff800000
	s_movk_i32 s78, 0x6000
	s_ashr_i32 s17, s16, 31
	s_lshl_b64 s[2:3], s[16:17], 18
	s_or_b32 s2, s2, s44
	v_lshl_add_u64 v[10:11], v[202:203], 0, s[2:3]
	v_lshl_add_u64 v[12:13], v[206:207], 0, s[2:3]
	s_bitset1_b32 s2, 15
	global_load_dwordx4 v[20:23], v[10:11], off
	global_load_dwordx4 v[24:27], v[10:11], off offset:64
	global_load_dwordx4 v[28:31], v[10:11], off offset:128
	global_load_dwordx4 v[32:35], v[10:11], off offset:192
	global_load_dwordx4 v[40:43], v[10:11], off offset:256
	global_load_dwordx4 v[48:51], v[10:11], off offset:320
	global_load_dwordx4 v[56:59], v[10:11], off offset:384
	global_load_dwordx4 v[64:67], v[10:11], off offset:448
	global_load_dwordx4 v[36:39], v[12:13], off
	global_load_dwordx4 v[44:47], v[12:13], off offset:256
	global_load_dwordx4 v[52:55], v[12:13], off offset:2048
	global_load_dwordx4 v[60:63], v[12:13], off offset:2304
	v_lshl_add_u64 v[10:11], v[202:203], 0, s[2:3]
	v_add_co_u32_e32 v12, vcc, s79, v12
	v_lshl_add_u64 v[14:15], v[206:207], 0, s[2:3]
	s_nop 0
	v_addc_co_u32_e32 v13, vcc, 0, v13, vcc
	global_load_dwordx4 v[68:71], v[10:11], off
	global_load_dwordx4 v[72:75], v[10:11], off offset:64
	global_load_dwordx4 v[76:79], v[10:11], off offset:128
	global_load_dwordx4 v[80:83], v[10:11], off offset:192
	global_load_dwordx4 v[88:91], v[10:11], off offset:256
	global_load_dwordx4 v[96:99], v[10:11], off offset:320
	global_load_dwordx4 v[104:107], v[10:11], off offset:384
	global_load_dwordx4 v[112:115], v[10:11], off offset:448
	global_load_dwordx4 v[84:87], v[14:15], off
	global_load_dwordx4 v[92:95], v[14:15], off offset:256
	global_load_dwordx4 v[100:103], v[14:15], off offset:2048
	global_load_dwordx4 v[108:111], v[14:15], off offset:2304
	global_load_dwordx4 v[116:119], v[12:13], off
	global_load_dwordx4 v[120:123], v[12:13], off offset:256
	global_load_dwordx4 v[124:127], v[12:13], off offset:2048
	global_load_dwordx4 v[128:131], v[12:13], off offset:2304
	v_add_co_u32_e32 v10, vcc, s79, v14
	s_waitcnt vmcnt(30)
	v_cndmask_b32_e64 v19, 0, v9, s[14:15]
	v_addc_co_u32_e32 v11, vcc, 0, v15, vcc
	global_load_dwordx4 v[132:135], v[10:11], off
	global_load_dwordx4 v[136:139], v[10:11], off offset:256
	global_load_dwordx4 v[140:143], v[10:11], off offset:2048
	global_load_dwordx4 v[144:147], v[10:11], off offset:2304
	v_cndmask_b32_e64 v18, 0, v8, s[14:15]
	v_cndmask_b32_e64 v17, 0, v7, s[14:15]
	v_cndmask_b32_e64 v16, 0, v6, s[14:15]
	s_waitcnt vmcnt(32)
	v_cndmask_b32_e64 v15, 0, v5, s[14:15]
	v_cndmask_b32_e64 v14, 0, v4, s[14:15]
	v_cndmask_b32_e64 v13, 0, v149, s[14:15]
	v_cndmask_b32_e64 v12, 0, v148, s[14:15]
	v_cndmask_b32_e64 v11, v9, 0, s[14:15]
	v_cndmask_b32_e64 v10, v8, 0, s[14:15]
	v_cndmask_b32_e64 v9, v7, 0, s[14:15]
	v_cndmask_b32_e64 v8, v6, 0, s[14:15]
	v_cndmask_b32_e64 v7, v5, 0, s[14:15]
	v_cndmask_b32_e64 v6, v4, 0, s[14:15]
	v_cndmask_b32_e64 v5, v149, 0, s[14:15]
	v_cndmask_b32_e64 v4, v148, 0, s[14:15]
	s_mov_b32 s64, s100
	v_mov_b32_e32 v0, v2
	v_mov_b32_e32 v1, v2
	v_mov_b64_e32 v[170:171], v[2:3]
	v_mov_b64_e32 v[174:175], v[2:3]
	v_mov_b64_e32 v[178:179], v[2:3]
	v_mov_b64_e32 v[166:167], v[2:3]
	v_mov_b64_e32 v[150:151], v[2:3]
	v_mov_b64_e32 v[154:155], v[2:3]
	v_mov_b64_e32 v[158:159], v[2:3]
	v_mov_b64_e32 v[162:163], v[2:3]
	s_mov_b32 s17, 0
	v_mov_b64_e32 v[168:169], v[0:1]
	v_mov_b64_e32 v[172:173], v[0:1]
	v_mov_b64_e32 v[176:177], v[0:1]
	v_mov_b64_e32 v[164:165], v[0:1]
	v_mov_b64_e32 v[148:149], v[0:1]
	v_mov_b64_e32 v[152:153], v[0:1]
	v_mov_b64_e32 v[156:157], v[0:1]
	v_mov_b64_e32 v[160:161], v[0:1]
	ds_write_b128 v237, v[16:19]
	ds_write_b128 v237, v[12:15] offset:1024
	ds_write_b128 v237, v[8:11] offset:2048
	ds_write_b128 v237, v[4:7] offset:3072
	s_branch .LBB0_387
